# v5 + G1/G5 hidden stores sc0 sc1 nt (write-through, dropped from L2)
# speedup vs baseline: 1.0032x; 1.0023x over previous
.LBB0_163:
	v_mov_b32_e32 v164, 0xbfb8aa3b
	s_lshl_b32 s5, s42, 7
	s_or_b32 s5, s5, s36
	s_mul_i32 s14, s41, 0x2c0000
	s_mul_hi_i32 s7, s41, 0x2c0000
	s_add_u32 s16, s34, s14
	s_addc_u32 s7, s35, s7
	s_ashr_i32 s14, s5, 6
	s_ashr_i32 s15, s14, 31
	s_lshl_b64 s[14:15], s[14:15], 15
	s_add_u32 s14, s16, s14
	s_addc_u32 s15, s7, s15
	v_lshl_add_u64 v[154:155], s[14:15], 0, v[2:3]
	v_lshl_add_u64 v[156:157], v[140:141], 1, v[154:155]
	s_mov_b64 s[14:15], -1
	s_movk_i32 s45, 0x3000
	s_mov_b32 s47, 0x11000
	s_mov_b32 s48, 0x9000
	v_pk_mul_f32 v[160:161], v[128:129], v[164:165] op_sel_hi:[1,0]
	v_pk_mul_f32 v[162:163], v[130:131], v[164:165] op_sel_hi:[1,0]
	v_exp_f32_e32 v160, v160
	v_exp_f32_e32 v161, v161
	v_exp_f32_e32 v162, v162
	v_exp_f32_e32 v163, v163
	v_pk_add_f32 v[160:161], v[160:161], 1.0 op_sel_hi:[1,0]
	v_pk_add_f32 v[162:163], v[162:163], 1.0 op_sel_hi:[1,0]
	v_rcp_f32_e32 v160, v160
	v_rcp_f32_e32 v161, v161
	v_rcp_f32_e32 v162, v162
	v_rcp_f32_e32 v163, v163
	v_pk_mul_f32 v[160:161], v[128:129], v[160:161]
	v_pk_mul_f32 v[162:163], v[130:131], v[162:163]
	v_pk_mul_f32 v[160:161], v[160:161], v[124:125]
	v_pk_mul_f32 v[162:163], v[162:163], v[126:127]
	v_cvt_pk_bf16_f32 v124, v160, v161
	v_cvt_pk_bf16_f32 v125, v162, v163
	v_pk_mul_f32 v[160:161], v[120:121], v[164:165] op_sel_hi:[1,0]
	v_pk_mul_f32 v[162:163], v[122:123], v[164:165] op_sel_hi:[1,0]
	v_exp_f32_e32 v160, v160
	v_exp_f32_e32 v161, v161
	v_exp_f32_e32 v162, v162
	v_exp_f32_e32 v163, v163
	v_pk_add_f32 v[160:161], v[160:161], 1.0 op_sel_hi:[1,0]
	v_pk_add_f32 v[162:163], v[162:163], 1.0 op_sel_hi:[1,0]
	v_rcp_f32_e32 v160, v160
	v_rcp_f32_e32 v161, v161
	v_rcp_f32_e32 v162, v162
	v_rcp_f32_e32 v163, v163
	v_pk_mul_f32 v[160:161], v[120:121], v[160:161]
	v_pk_mul_f32 v[162:163], v[122:123], v[162:163]
	v_pk_mul_f32 v[160:161], v[160:161], v[116:117]
	v_pk_mul_f32 v[162:163], v[162:163], v[118:119]
	v_cvt_pk_bf16_f32 v126, v160, v161
	v_cvt_pk_bf16_f32 v127, v162, v163
	global_store_dwordx4 v[156:157], v[124:127], off sc0 sc1 nt
	v_pk_mul_f32 v[160:161], v[112:113], v[164:165] op_sel_hi:[1,0]
	v_pk_mul_f32 v[162:163], v[114:115], v[164:165] op_sel_hi:[1,0]
	v_exp_f32_e32 v160, v160
	v_exp_f32_e32 v161, v161
	v_exp_f32_e32 v162, v162
	v_exp_f32_e32 v163, v163
	v_pk_add_f32 v[160:161], v[160:161], 1.0 op_sel_hi:[1,0]
	v_pk_add_f32 v[162:163], v[162:163], 1.0 op_sel_hi:[1,0]
	v_rcp_f32_e32 v160, v160
	v_rcp_f32_e32 v161, v161
	v_rcp_f32_e32 v162, v162
	v_rcp_f32_e32 v163, v163
	v_pk_mul_f32 v[160:161], v[112:113], v[160:161]
	v_pk_mul_f32 v[162:163], v[114:115], v[162:163]
	v_pk_mul_f32 v[160:161], v[160:161], v[108:109]
	v_pk_mul_f32 v[162:163], v[162:163], v[110:111]
	v_cvt_pk_bf16_f32 v108, v160, v161
	v_cvt_pk_bf16_f32 v109, v162, v163
	v_pk_mul_f32 v[160:161], v[104:105], v[164:165] op_sel_hi:[1,0]
	v_pk_mul_f32 v[162:163], v[106:107], v[164:165] op_sel_hi:[1,0]
	v_exp_f32_e32 v160, v160
	v_exp_f32_e32 v161, v161
	v_exp_f32_e32 v162, v162
	v_exp_f32_e32 v163, v163
	v_pk_add_f32 v[160:161], v[160:161], 1.0 op_sel_hi:[1,0]
	v_pk_add_f32 v[162:163], v[162:163], 1.0 op_sel_hi:[1,0]
	v_rcp_f32_e32 v160, v160
	v_rcp_f32_e32 v161, v161
	v_rcp_f32_e32 v162, v162
	v_rcp_f32_e32 v163, v163
	v_pk_mul_f32 v[160:161], v[104:105], v[160:161]
	v_pk_mul_f32 v[162:163], v[106:107], v[162:163]
	v_pk_mul_f32 v[160:161], v[160:161], v[100:101]
	v_pk_mul_f32 v[162:163], v[162:163], v[102:103]
	v_cvt_pk_bf16_f32 v110, v160, v161
	v_cvt_pk_bf16_f32 v111, v162, v163
	global_store_dwordx4 v[156:157], v[108:111], off offset:2048 sc0 sc1 nt
	v_pk_mul_f32 v[160:161], v[96:97], v[164:165] op_sel_hi:[1,0]
	v_pk_mul_f32 v[162:163], v[98:99], v[164:165] op_sel_hi:[1,0]
	v_exp_f32_e32 v160, v160
	v_exp_f32_e32 v161, v161
	v_exp_f32_e32 v162, v162
	v_exp_f32_e32 v163, v163
	v_pk_add_f32 v[160:161], v[160:161], 1.0 op_sel_hi:[1,0]
	v_pk_add_f32 v[162:163], v[162:163], 1.0 op_sel_hi:[1,0]
	v_rcp_f32_e32 v160, v160
	v_rcp_f32_e32 v161, v161
	v_rcp_f32_e32 v162, v162
	v_rcp_f32_e32 v163, v163
	v_pk_mul_f32 v[160:161], v[96:97], v[160:161]
	v_pk_mul_f32 v[162:163], v[98:99], v[162:163]
	v_pk_mul_f32 v[160:161], v[160:161], v[92:93]
	v_pk_mul_f32 v[162:163], v[162:163], v[94:95]
	v_cvt_pk_bf16_f32 v92, v160, v161
	v_cvt_pk_bf16_f32 v93, v162, v163
	v_pk_mul_f32 v[160:161], v[88:89], v[164:165] op_sel_hi:[1,0]
	v_pk_mul_f32 v[162:163], v[90:91], v[164:165] op_sel_hi:[1,0]
	v_exp_f32_e32 v160, v160
	v_exp_f32_e32 v161, v161
	v_exp_f32_e32 v162, v162
	v_exp_f32_e32 v163, v163
	v_pk_add_f32 v[160:161], v[160:161], 1.0 op_sel_hi:[1,0]
	v_pk_add_f32 v[162:163], v[162:163], 1.0 op_sel_hi:[1,0]
	v_rcp_f32_e32 v160, v160
	v_rcp_f32_e32 v161, v161
	v_rcp_f32_e32 v162, v162
	v_rcp_f32_e32 v163, v163
	v_pk_mul_f32 v[160:161], v[88:89], v[160:161]
	v_pk_mul_f32 v[162:163], v[90:91], v[162:163]
	v_pk_mul_f32 v[160:161], v[160:161], v[84:85]
	v_pk_mul_f32 v[162:163], v[162:163], v[86:87]
	v_cvt_pk_bf16_f32 v94, v160, v161
	v_cvt_pk_bf16_f32 v95, v162, v163
	v_add_co_u32_e32 v84, vcc, s51, v156
	s_nop 1
	v_addc_co_u32_e32 v85, vcc, 0, v157, vcc
	global_store_dwordx4 v[84:85], v[92:95], off sc0 sc1 nt
	s_andn2_b64 vcc, exec, s[8:9]
	v_pk_mul_f32 v[160:161], v[80:81], v[164:165] op_sel_hi:[1,0]
	v_pk_mul_f32 v[162:163], v[82:83], v[164:165] op_sel_hi:[1,0]
	v_exp_f32_e32 v160, v160
	v_exp_f32_e32 v161, v161
	v_exp_f32_e32 v162, v162
	v_exp_f32_e32 v163, v163
	v_pk_add_f32 v[160:161], v[160:161], 1.0 op_sel_hi:[1,0]
	v_pk_add_f32 v[162:163], v[162:163], 1.0 op_sel_hi:[1,0]
	v_rcp_f32_e32 v160, v160
	v_rcp_f32_e32 v161, v161
	v_rcp_f32_e32 v162, v162
	v_rcp_f32_e32 v163, v163
	v_pk_mul_f32 v[160:161], v[80:81], v[160:161]
	v_pk_mul_f32 v[162:163], v[82:83], v[162:163]
	v_pk_mul_f32 v[160:161], v[160:161], v[76:77]
	v_pk_mul_f32 v[162:163], v[162:163], v[78:79]
	v_cvt_pk_bf16_f32 v76, v160, v161
	v_cvt_pk_bf16_f32 v77, v162, v163
	v_pk_mul_f32 v[160:161], v[72:73], v[164:165] op_sel_hi:[1,0]
	v_pk_mul_f32 v[162:163], v[74:75], v[164:165] op_sel_hi:[1,0]
	v_exp_f32_e32 v160, v160
	v_exp_f32_e32 v161, v161
	v_exp_f32_e32 v162, v162
	v_exp_f32_e32 v163, v163
	v_pk_add_f32 v[160:161], v[160:161], 1.0 op_sel_hi:[1,0]
	v_pk_add_f32 v[162:163], v[162:163], 1.0 op_sel_hi:[1,0]
	v_rcp_f32_e32 v160, v160
	v_rcp_f32_e32 v161, v161
	v_rcp_f32_e32 v162, v162
	v_rcp_f32_e32 v163, v163
	v_pk_mul_f32 v[160:161], v[72:73], v[160:161]
	v_pk_mul_f32 v[162:163], v[74:75], v[162:163]
	v_pk_mul_f32 v[160:161], v[160:161], v[68:69]
	v_pk_mul_f32 v[162:163], v[162:163], v[70:71]
	v_cvt_pk_bf16_f32 v78, v160, v161
	v_cvt_pk_bf16_f32 v79, v162, v163
	global_store_dwordx4 v[84:85], v[76:79], off offset:2048 sc0 sc1 nt
	v_lshl_add_u64 v[68:69], v[142:143], 1, v[154:155]
	v_pk_mul_f32 v[160:161], v[64:65], v[164:165] op_sel_hi:[1,0]
	v_pk_mul_f32 v[162:163], v[66:67], v[164:165] op_sel_hi:[1,0]
	v_exp_f32_e32 v160, v160
	v_exp_f32_e32 v161, v161
	v_exp_f32_e32 v162, v162
	v_exp_f32_e32 v163, v163
	v_pk_add_f32 v[160:161], v[160:161], 1.0 op_sel_hi:[1,0]
	v_pk_add_f32 v[162:163], v[162:163], 1.0 op_sel_hi:[1,0]
	v_rcp_f32_e32 v160, v160
	v_rcp_f32_e32 v161, v161
	v_rcp_f32_e32 v162, v162
	v_rcp_f32_e32 v163, v163
	v_pk_mul_f32 v[160:161], v[64:65], v[160:161]
	v_pk_mul_f32 v[162:163], v[66:67], v[162:163]
	v_pk_mul_f32 v[160:161], v[160:161], v[60:61]
	v_pk_mul_f32 v[162:163], v[162:163], v[62:63]
	v_cvt_pk_bf16_f32 v60, v160, v161
	v_cvt_pk_bf16_f32 v61, v162, v163
	v_pk_mul_f32 v[160:161], v[56:57], v[164:165] op_sel_hi:[1,0]
	v_pk_mul_f32 v[162:163], v[58:59], v[164:165] op_sel_hi:[1,0]
	v_exp_f32_e32 v160, v160
	v_exp_f32_e32 v161, v161
	v_exp_f32_e32 v162, v162
	v_exp_f32_e32 v163, v163
	v_pk_add_f32 v[160:161], v[160:161], 1.0 op_sel_hi:[1,0]
	v_pk_add_f32 v[162:163], v[162:163], 1.0 op_sel_hi:[1,0]
	v_rcp_f32_e32 v160, v160
	v_rcp_f32_e32 v161, v161
	v_rcp_f32_e32 v162, v162
	v_rcp_f32_e32 v163, v163
	v_pk_mul_f32 v[160:161], v[56:57], v[160:161]
	v_pk_mul_f32 v[162:163], v[58:59], v[162:163]
	v_pk_mul_f32 v[160:161], v[160:161], v[52:53]
	v_pk_mul_f32 v[162:163], v[162:163], v[54:55]
	v_cvt_pk_bf16_f32 v62, v160, v161
	v_cvt_pk_bf16_f32 v63, v162, v163
	global_store_dwordx4 v[68:69], v[60:63], off sc0 sc1 nt
	v_lshl_add_u64 v[52:53], v[144:145], 1, v[154:155]
	v_pk_mul_f32 v[160:161], v[48:49], v[164:165] op_sel_hi:[1,0]
	v_pk_mul_f32 v[162:163], v[50:51], v[164:165] op_sel_hi:[1,0]
	v_exp_f32_e32 v160, v160
	v_exp_f32_e32 v161, v161
	v_exp_f32_e32 v162, v162
	v_exp_f32_e32 v163, v163
	v_pk_add_f32 v[160:161], v[160:161], 1.0 op_sel_hi:[1,0]
	v_pk_add_f32 v[162:163], v[162:163], 1.0 op_sel_hi:[1,0]
	v_rcp_f32_e32 v160, v160
	v_rcp_f32_e32 v161, v161
	v_rcp_f32_e32 v162, v162
	v_rcp_f32_e32 v163, v163
	v_pk_mul_f32 v[160:161], v[48:49], v[160:161]
	v_pk_mul_f32 v[162:163], v[50:51], v[162:163]
	v_pk_mul_f32 v[160:161], v[160:161], v[44:45]
	v_pk_mul_f32 v[162:163], v[162:163], v[46:47]
	v_cvt_pk_bf16_f32 v44, v160, v161
	v_cvt_pk_bf16_f32 v45, v162, v163
	v_pk_mul_f32 v[160:161], v[40:41], v[164:165] op_sel_hi:[1,0]
	v_pk_mul_f32 v[162:163], v[42:43], v[164:165] op_sel_hi:[1,0]
	v_exp_f32_e32 v160, v160
	v_exp_f32_e32 v161, v161
	v_exp_f32_e32 v162, v162
	v_exp_f32_e32 v163, v163
	v_pk_add_f32 v[160:161], v[160:161], 1.0 op_sel_hi:[1,0]
	v_pk_add_f32 v[162:163], v[162:163], 1.0 op_sel_hi:[1,0]
	v_rcp_f32_e32 v160, v160
	v_rcp_f32_e32 v161, v161
	v_rcp_f32_e32 v162, v162
	v_rcp_f32_e32 v163, v163
	v_pk_mul_f32 v[160:161], v[40:41], v[160:161]
	v_pk_mul_f32 v[162:163], v[42:43], v[162:163]
	v_pk_mul_f32 v[160:161], v[160:161], v[36:37]
	v_pk_mul_f32 v[162:163], v[162:163], v[38:39]
	v_cvt_pk_bf16_f32 v46, v160, v161
	v_cvt_pk_bf16_f32 v47, v162, v163
	global_store_dwordx4 v[52:53], v[44:47], off sc0 sc1 nt
	v_lshl_add_u64 v[36:37], v[146:147], 1, v[154:155]
	v_pk_mul_f32 v[160:161], v[32:33], v[164:165] op_sel_hi:[1,0]
	v_pk_mul_f32 v[162:163], v[34:35], v[164:165] op_sel_hi:[1,0]
	v_exp_f32_e32 v160, v160
	v_exp_f32_e32 v161, v161
	v_exp_f32_e32 v162, v162
	v_exp_f32_e32 v163, v163
	v_pk_add_f32 v[160:161], v[160:161], 1.0 op_sel_hi:[1,0]
	v_pk_add_f32 v[162:163], v[162:163], 1.0 op_sel_hi:[1,0]
	v_rcp_f32_e32 v160, v160
	v_rcp_f32_e32 v161, v161
	v_rcp_f32_e32 v162, v162
	v_rcp_f32_e32 v163, v163
	v_pk_mul_f32 v[160:161], v[32:33], v[160:161]
	v_pk_mul_f32 v[162:163], v[34:35], v[162:163]
	v_pk_mul_f32 v[160:161], v[160:161], v[28:29]
	v_pk_mul_f32 v[162:163], v[162:163], v[30:31]
	v_cvt_pk_bf16_f32 v28, v160, v161
	v_cvt_pk_bf16_f32 v29, v162, v163
	v_pk_mul_f32 v[160:161], v[24:25], v[164:165] op_sel_hi:[1,0]
	v_pk_mul_f32 v[162:163], v[26:27], v[164:165] op_sel_hi:[1,0]
	v_exp_f32_e32 v160, v160
	v_exp_f32_e32 v161, v161
	v_exp_f32_e32 v162, v162
	v_exp_f32_e32 v163, v163
	v_pk_add_f32 v[160:161], v[160:161], 1.0 op_sel_hi:[1,0]
	v_pk_add_f32 v[162:163], v[162:163], 1.0 op_sel_hi:[1,0]
	v_rcp_f32_e32 v160, v160
	v_rcp_f32_e32 v161, v161
	v_rcp_f32_e32 v162, v162
	v_rcp_f32_e32 v163, v163
	v_pk_mul_f32 v[160:161], v[24:25], v[160:161]
	v_pk_mul_f32 v[162:163], v[26:27], v[162:163]
	v_pk_mul_f32 v[160:161], v[160:161], v[20:21]
	v_pk_mul_f32 v[162:163], v[162:163], v[22:23]
	v_cvt_pk_bf16_f32 v30, v160, v161
	v_cvt_pk_bf16_f32 v31, v162, v163
	global_store_dwordx4 v[36:37], v[28:31], off sc0 sc1 nt
	v_lshl_add_u64 v[20:21], v[148:149], 1, v[154:155]
	v_pk_mul_f32 v[160:161], v[16:17], v[164:165] op_sel_hi:[1,0]
	v_pk_mul_f32 v[162:163], v[18:19], v[164:165] op_sel_hi:[1,0]
	v_exp_f32_e32 v160, v160
	v_exp_f32_e32 v161, v161
	v_exp_f32_e32 v162, v162
	v_exp_f32_e32 v163, v163
	v_pk_add_f32 v[160:161], v[160:161], 1.0 op_sel_hi:[1,0]
	v_pk_add_f32 v[162:163], v[162:163], 1.0 op_sel_hi:[1,0]
	v_rcp_f32_e32 v160, v160
	v_rcp_f32_e32 v161, v161
	v_rcp_f32_e32 v162, v162
	v_rcp_f32_e32 v163, v163
	v_pk_mul_f32 v[160:161], v[16:17], v[160:161]
	v_pk_mul_f32 v[162:163], v[18:19], v[162:163]
	v_pk_mul_f32 v[160:161], v[160:161], v[12:13]
	v_pk_mul_f32 v[162:163], v[162:163], v[14:15]
	v_cvt_pk_bf16_f32 v12, v160, v161
	v_cvt_pk_bf16_f32 v13, v162, v163
	v_pk_mul_f32 v[160:161], v[8:9], v[164:165] op_sel_hi:[1,0]
	v_pk_mul_f32 v[162:163], v[10:11], v[164:165] op_sel_hi:[1,0]
	v_exp_f32_e32 v160, v160
	v_exp_f32_e32 v161, v161
	v_exp_f32_e32 v162, v162
	v_exp_f32_e32 v163, v163
	v_pk_add_f32 v[160:161], v[160:161], 1.0 op_sel_hi:[1,0]
	v_pk_add_f32 v[162:163], v[162:163], 1.0 op_sel_hi:[1,0]
	v_rcp_f32_e32 v160, v160
	v_rcp_f32_e32 v161, v161
	v_rcp_f32_e32 v162, v162
	v_rcp_f32_e32 v163, v163
	v_pk_mul_f32 v[160:161], v[8:9], v[160:161]
	v_pk_mul_f32 v[162:163], v[10:11], v[162:163]
	v_pk_mul_f32 v[160:161], v[160:161], v[4:5]
	v_pk_mul_f32 v[162:163], v[162:163], v[6:7]
	v_cvt_pk_bf16_f32 v14, v160, v161
	v_cvt_pk_bf16_f32 v15, v162, v163
	global_store_dwordx4 v[20:21], v[12:15], off sc0 sc1 nt
	s_cbranch_vccnz .LBB0_156
	s_andn2_b64 vcc, exec, s[0:1]
	s_cbranch_vccnz .LBB0_155
	s_barrier
	s_branch .LBB0_155

.LBB0_747:
	v_mov_b32_e32 v164, 0xbfb8aa3b
	s_lshl_b32 s7, s44, 7
	s_or_b32 s7, s7, s38
	s_mul_i32 s16, s43, 0x2c0000
	s_mul_hi_i32 s11, s43, 0x2c0000
	s_add_u32 s18, s36, s16
	s_addc_u32 s11, s37, s11
	s_ashr_i32 s16, s7, 6
	s_ashr_i32 s17, s16, 31
	s_lshl_b64 s[16:17], s[16:17], 15
	s_add_u32 s16, s18, s16
	s_addc_u32 s17, s11, s17
	v_lshl_add_u64 v[154:155], s[16:17], 0, v[2:3]
	v_lshl_add_u64 v[156:157], v[140:141], 1, v[154:155]
	s_mov_b64 s[16:17], -1
	s_movk_i32 s45, 0x3000
	s_mov_b32 s47, 0x11000
	s_mov_b32 s48, 0x9000
	v_pk_mul_f32 v[160:161], v[128:129], v[164:165] op_sel_hi:[1,0]
	v_pk_mul_f32 v[162:163], v[130:131], v[164:165] op_sel_hi:[1,0]
	v_exp_f32_e32 v160, v160
	v_exp_f32_e32 v161, v161
	v_exp_f32_e32 v162, v162
	v_exp_f32_e32 v163, v163
	v_pk_add_f32 v[160:161], v[160:161], 1.0 op_sel_hi:[1,0]
	v_pk_add_f32 v[162:163], v[162:163], 1.0 op_sel_hi:[1,0]
	v_rcp_f32_e32 v160, v160
	v_rcp_f32_e32 v161, v161
	v_rcp_f32_e32 v162, v162
	v_rcp_f32_e32 v163, v163
	v_pk_mul_f32 v[160:161], v[128:129], v[160:161]
	v_pk_mul_f32 v[162:163], v[130:131], v[162:163]
	v_pk_mul_f32 v[160:161], v[160:161], v[124:125]
	v_pk_mul_f32 v[162:163], v[162:163], v[126:127]
	v_cvt_pk_bf16_f32 v124, v160, v161
	v_cvt_pk_bf16_f32 v125, v162, v163
	v_pk_mul_f32 v[160:161], v[120:121], v[164:165] op_sel_hi:[1,0]
	v_pk_mul_f32 v[162:163], v[122:123], v[164:165] op_sel_hi:[1,0]
	v_exp_f32_e32 v160, v160
	v_exp_f32_e32 v161, v161
	v_exp_f32_e32 v162, v162
	v_exp_f32_e32 v163, v163
	v_pk_add_f32 v[160:161], v[160:161], 1.0 op_sel_hi:[1,0]
	v_pk_add_f32 v[162:163], v[162:163], 1.0 op_sel_hi:[1,0]
	v_rcp_f32_e32 v160, v160
	v_rcp_f32_e32 v161, v161
	v_rcp_f32_e32 v162, v162
	v_rcp_f32_e32 v163, v163
	v_pk_mul_f32 v[160:161], v[120:121], v[160:161]
	v_pk_mul_f32 v[162:163], v[122:123], v[162:163]
	v_pk_mul_f32 v[160:161], v[160:161], v[116:117]
	v_pk_mul_f32 v[162:163], v[162:163], v[118:119]
	v_cvt_pk_bf16_f32 v126, v160, v161
	v_cvt_pk_bf16_f32 v127, v162, v163
	global_store_dwordx4 v[156:157], v[124:127], off sc0 sc1 nt
	v_pk_mul_f32 v[160:161], v[112:113], v[164:165] op_sel_hi:[1,0]
	v_pk_mul_f32 v[162:163], v[114:115], v[164:165] op_sel_hi:[1,0]
	v_exp_f32_e32 v160, v160
	v_exp_f32_e32 v161, v161
	v_exp_f32_e32 v162, v162
	v_exp_f32_e32 v163, v163
	v_pk_add_f32 v[160:161], v[160:161], 1.0 op_sel_hi:[1,0]
	v_pk_add_f32 v[162:163], v[162:163], 1.0 op_sel_hi:[1,0]
	v_rcp_f32_e32 v160, v160
	v_rcp_f32_e32 v161, v161
	v_rcp_f32_e32 v162, v162
	v_rcp_f32_e32 v163, v163
	v_pk_mul_f32 v[160:161], v[112:113], v[160:161]
	v_pk_mul_f32 v[162:163], v[114:115], v[162:163]
	v_pk_mul_f32 v[160:161], v[160:161], v[108:109]
	v_pk_mul_f32 v[162:163], v[162:163], v[110:111]
	v_cvt_pk_bf16_f32 v108, v160, v161
	v_cvt_pk_bf16_f32 v109, v162, v163
	v_pk_mul_f32 v[160:161], v[104:105], v[164:165] op_sel_hi:[1,0]
	v_pk_mul_f32 v[162:163], v[106:107], v[164:165] op_sel_hi:[1,0]
	v_exp_f32_e32 v160, v160
	v_exp_f32_e32 v161, v161
	v_exp_f32_e32 v162, v162
	v_exp_f32_e32 v163, v163
	v_pk_add_f32 v[160:161], v[160:161], 1.0 op_sel_hi:[1,0]
	v_pk_add_f32 v[162:163], v[162:163], 1.0 op_sel_hi:[1,0]
	v_rcp_f32_e32 v160, v160
	v_rcp_f32_e32 v161, v161
	v_rcp_f32_e32 v162, v162
	v_rcp_f32_e32 v163, v163
	v_pk_mul_f32 v[160:161], v[104:105], v[160:161]
	v_pk_mul_f32 v[162:163], v[106:107], v[162:163]
	v_pk_mul_f32 v[160:161], v[160:161], v[100:101]
	v_pk_mul_f32 v[162:163], v[162:163], v[102:103]
	v_cvt_pk_bf16_f32 v110, v160, v161
	v_cvt_pk_bf16_f32 v111, v162, v163
	global_store_dwordx4 v[156:157], v[108:111], off offset:2048 sc0 sc1 nt
	v_pk_mul_f32 v[160:161], v[96:97], v[164:165] op_sel_hi:[1,0]
	v_pk_mul_f32 v[162:163], v[98:99], v[164:165] op_sel_hi:[1,0]
	v_exp_f32_e32 v160, v160
	v_exp_f32_e32 v161, v161
	v_exp_f32_e32 v162, v162
	v_exp_f32_e32 v163, v163
	v_pk_add_f32 v[160:161], v[160:161], 1.0 op_sel_hi:[1,0]
	v_pk_add_f32 v[162:163], v[162:163], 1.0 op_sel_hi:[1,0]
	v_rcp_f32_e32 v160, v160
	v_rcp_f32_e32 v161, v161
	v_rcp_f32_e32 v162, v162
	v_rcp_f32_e32 v163, v163
	v_pk_mul_f32 v[160:161], v[96:97], v[160:161]
	v_pk_mul_f32 v[162:163], v[98:99], v[162:163]
	v_pk_mul_f32 v[160:161], v[160:161], v[92:93]
	v_pk_mul_f32 v[162:163], v[162:163], v[94:95]
	v_cvt_pk_bf16_f32 v92, v160, v161
	v_cvt_pk_bf16_f32 v93, v162, v163
	v_pk_mul_f32 v[160:161], v[88:89], v[164:165] op_sel_hi:[1,0]
	v_pk_mul_f32 v[162:163], v[90:91], v[164:165] op_sel_hi:[1,0]
	v_exp_f32_e32 v160, v160
	v_exp_f32_e32 v161, v161
	v_exp_f32_e32 v162, v162
	v_exp_f32_e32 v163, v163
	v_pk_add_f32 v[160:161], v[160:161], 1.0 op_sel_hi:[1,0]
	v_pk_add_f32 v[162:163], v[162:163], 1.0 op_sel_hi:[1,0]
	v_rcp_f32_e32 v160, v160
	v_rcp_f32_e32 v161, v161
	v_rcp_f32_e32 v162, v162
	v_rcp_f32_e32 v163, v163
	v_pk_mul_f32 v[160:161], v[88:89], v[160:161]
	v_pk_mul_f32 v[162:163], v[90:91], v[162:163]
	v_pk_mul_f32 v[160:161], v[160:161], v[84:85]
	v_pk_mul_f32 v[162:163], v[162:163], v[86:87]
	v_cvt_pk_bf16_f32 v94, v160, v161
	v_cvt_pk_bf16_f32 v95, v162, v163
	v_add_co_u32_e32 v84, vcc, s53, v156
	s_nop 1
	v_addc_co_u32_e32 v85, vcc, 0, v157, vcc
	global_store_dwordx4 v[84:85], v[92:95], off sc0 sc1 nt
	s_andn2_b64 vcc, exec, s[8:9]
	v_pk_mul_f32 v[160:161], v[80:81], v[164:165] op_sel_hi:[1,0]
	v_pk_mul_f32 v[162:163], v[82:83], v[164:165] op_sel_hi:[1,0]
	v_exp_f32_e32 v160, v160
	v_exp_f32_e32 v161, v161
	v_exp_f32_e32 v162, v162
	v_exp_f32_e32 v163, v163
	v_pk_add_f32 v[160:161], v[160:161], 1.0 op_sel_hi:[1,0]
	v_pk_add_f32 v[162:163], v[162:163], 1.0 op_sel_hi:[1,0]
	v_rcp_f32_e32 v160, v160
	v_rcp_f32_e32 v161, v161
	v_rcp_f32_e32 v162, v162
	v_rcp_f32_e32 v163, v163
	v_pk_mul_f32 v[160:161], v[80:81], v[160:161]
	v_pk_mul_f32 v[162:163], v[82:83], v[162:163]
	v_pk_mul_f32 v[160:161], v[160:161], v[76:77]
	v_pk_mul_f32 v[162:163], v[162:163], v[78:79]
	v_cvt_pk_bf16_f32 v76, v160, v161
	v_cvt_pk_bf16_f32 v77, v162, v163
	v_pk_mul_f32 v[160:161], v[72:73], v[164:165] op_sel_hi:[1,0]
	v_pk_mul_f32 v[162:163], v[74:75], v[164:165] op_sel_hi:[1,0]
	v_exp_f32_e32 v160, v160
	v_exp_f32_e32 v161, v161
	v_exp_f32_e32 v162, v162
	v_exp_f32_e32 v163, v163
	v_pk_add_f32 v[160:161], v[160:161], 1.0 op_sel_hi:[1,0]
	v_pk_add_f32 v[162:163], v[162:163], 1.0 op_sel_hi:[1,0]
	v_rcp_f32_e32 v160, v160
	v_rcp_f32_e32 v161, v161
	v_rcp_f32_e32 v162, v162
	v_rcp_f32_e32 v163, v163
	v_pk_mul_f32 v[160:161], v[72:73], v[160:161]
	v_pk_mul_f32 v[162:163], v[74:75], v[162:163]
	v_pk_mul_f32 v[160:161], v[160:161], v[68:69]
	v_pk_mul_f32 v[162:163], v[162:163], v[70:71]
	v_cvt_pk_bf16_f32 v78, v160, v161
	v_cvt_pk_bf16_f32 v79, v162, v163
	global_store_dwordx4 v[84:85], v[76:79], off offset:2048 sc0 sc1 nt
	v_lshl_add_u64 v[68:69], v[142:143], 1, v[154:155]
	v_pk_mul_f32 v[160:161], v[64:65], v[164:165] op_sel_hi:[1,0]
	v_pk_mul_f32 v[162:163], v[66:67], v[164:165] op_sel_hi:[1,0]
	v_exp_f32_e32 v160, v160
	v_exp_f32_e32 v161, v161
	v_exp_f32_e32 v162, v162
	v_exp_f32_e32 v163, v163
	v_pk_add_f32 v[160:161], v[160:161], 1.0 op_sel_hi:[1,0]
	v_pk_add_f32 v[162:163], v[162:163], 1.0 op_sel_hi:[1,0]
	v_rcp_f32_e32 v160, v160
	v_rcp_f32_e32 v161, v161
	v_rcp_f32_e32 v162, v162
	v_rcp_f32_e32 v163, v163
	v_pk_mul_f32 v[160:161], v[64:65], v[160:161]
	v_pk_mul_f32 v[162:163], v[66:67], v[162:163]
	v_pk_mul_f32 v[160:161], v[160:161], v[60:61]
	v_pk_mul_f32 v[162:163], v[162:163], v[62:63]
	v_cvt_pk_bf16_f32 v60, v160, v161
	v_cvt_pk_bf16_f32 v61, v162, v163
	v_pk_mul_f32 v[160:161], v[56:57], v[164:165] op_sel_hi:[1,0]
	v_pk_mul_f32 v[162:163], v[58:59], v[164:165] op_sel_hi:[1,0]
	v_exp_f32_e32 v160, v160
	v_exp_f32_e32 v161, v161
	v_exp_f32_e32 v162, v162
	v_exp_f32_e32 v163, v163
	v_pk_add_f32 v[160:161], v[160:161], 1.0 op_sel_hi:[1,0]
	v_pk_add_f32 v[162:163], v[162:163], 1.0 op_sel_hi:[1,0]
	v_rcp_f32_e32 v160, v160
	v_rcp_f32_e32 v161, v161
	v_rcp_f32_e32 v162, v162
	v_rcp_f32_e32 v163, v163
	v_pk_mul_f32 v[160:161], v[56:57], v[160:161]
	v_pk_mul_f32 v[162:163], v[58:59], v[162:163]
	v_pk_mul_f32 v[160:161], v[160:161], v[52:53]
	v_pk_mul_f32 v[162:163], v[162:163], v[54:55]
	v_cvt_pk_bf16_f32 v62, v160, v161
	v_cvt_pk_bf16_f32 v63, v162, v163
	global_store_dwordx4 v[68:69], v[60:63], off sc0 sc1 nt
	v_lshl_add_u64 v[52:53], v[144:145], 1, v[154:155]
	v_pk_mul_f32 v[160:161], v[48:49], v[164:165] op_sel_hi:[1,0]
	v_pk_mul_f32 v[162:163], v[50:51], v[164:165] op_sel_hi:[1,0]
	v_exp_f32_e32 v160, v160
	v_exp_f32_e32 v161, v161
	v_exp_f32_e32 v162, v162
	v_exp_f32_e32 v163, v163
	v_pk_add_f32 v[160:161], v[160:161], 1.0 op_sel_hi:[1,0]
	v_pk_add_f32 v[162:163], v[162:163], 1.0 op_sel_hi:[1,0]
	v_rcp_f32_e32 v160, v160
	v_rcp_f32_e32 v161, v161
	v_rcp_f32_e32 v162, v162
	v_rcp_f32_e32 v163, v163
	v_pk_mul_f32 v[160:161], v[48:49], v[160:161]
	v_pk_mul_f32 v[162:163], v[50:51], v[162:163]
	v_pk_mul_f32 v[160:161], v[160:161], v[44:45]
	v_pk_mul_f32 v[162:163], v[162:163], v[46:47]
	v_cvt_pk_bf16_f32 v44, v160, v161
	v_cvt_pk_bf16_f32 v45, v162, v163
	v_pk_mul_f32 v[160:161], v[40:41], v[164:165] op_sel_hi:[1,0]
	v_pk_mul_f32 v[162:163], v[42:43], v[164:165] op_sel_hi:[1,0]
	v_exp_f32_e32 v160, v160
	v_exp_f32_e32 v161, v161
	v_exp_f32_e32 v162, v162
	v_exp_f32_e32 v163, v163
	v_pk_add_f32 v[160:161], v[160:161], 1.0 op_sel_hi:[1,0]
	v_pk_add_f32 v[162:163], v[162:163], 1.0 op_sel_hi:[1,0]
	v_rcp_f32_e32 v160, v160
	v_rcp_f32_e32 v161, v161
	v_rcp_f32_e32 v162, v162
	v_rcp_f32_e32 v163, v163
	v_pk_mul_f32 v[160:161], v[40:41], v[160:161]
	v_pk_mul_f32 v[162:163], v[42:43], v[162:163]
	v_pk_mul_f32 v[160:161], v[160:161], v[36:37]
	v_pk_mul_f32 v[162:163], v[162:163], v[38:39]
	v_cvt_pk_bf16_f32 v46, v160, v161
	v_cvt_pk_bf16_f32 v47, v162, v163
	global_store_dwordx4 v[52:53], v[44:47], off sc0 sc1 nt
	v_lshl_add_u64 v[36:37], v[146:147], 1, v[154:155]
	v_pk_mul_f32 v[160:161], v[32:33], v[164:165] op_sel_hi:[1,0]
	v_pk_mul_f32 v[162:163], v[34:35], v[164:165] op_sel_hi:[1,0]
	v_exp_f32_e32 v160, v160
	v_exp_f32_e32 v161, v161
	v_exp_f32_e32 v162, v162
	v_exp_f32_e32 v163, v163
	v_pk_add_f32 v[160:161], v[160:161], 1.0 op_sel_hi:[1,0]
	v_pk_add_f32 v[162:163], v[162:163], 1.0 op_sel_hi:[1,0]
	v_rcp_f32_e32 v160, v160
	v_rcp_f32_e32 v161, v161
	v_rcp_f32_e32 v162, v162
	v_rcp_f32_e32 v163, v163
	v_pk_mul_f32 v[160:161], v[32:33], v[160:161]
	v_pk_mul_f32 v[162:163], v[34:35], v[162:163]
	v_pk_mul_f32 v[160:161], v[160:161], v[28:29]
	v_pk_mul_f32 v[162:163], v[162:163], v[30:31]
	v_cvt_pk_bf16_f32 v28, v160, v161
	v_cvt_pk_bf16_f32 v29, v162, v163
	v_pk_mul_f32 v[160:161], v[24:25], v[164:165] op_sel_hi:[1,0]
	v_pk_mul_f32 v[162:163], v[26:27], v[164:165] op_sel_hi:[1,0]
	v_exp_f32_e32 v160, v160
	v_exp_f32_e32 v161, v161
	v_exp_f32_e32 v162, v162
	v_exp_f32_e32 v163, v163
	v_pk_add_f32 v[160:161], v[160:161], 1.0 op_sel_hi:[1,0]
	v_pk_add_f32 v[162:163], v[162:163], 1.0 op_sel_hi:[1,0]
	v_rcp_f32_e32 v160, v160
	v_rcp_f32_e32 v161, v161
	v_rcp_f32_e32 v162, v162
	v_rcp_f32_e32 v163, v163
	v_pk_mul_f32 v[160:161], v[24:25], v[160:161]
	v_pk_mul_f32 v[162:163], v[26:27], v[162:163]
	v_pk_mul_f32 v[160:161], v[160:161], v[20:21]
	v_pk_mul_f32 v[162:163], v[162:163], v[22:23]
	v_cvt_pk_bf16_f32 v30, v160, v161
	v_cvt_pk_bf16_f32 v31, v162, v163
	global_store_dwordx4 v[36:37], v[28:31], off sc0 sc1 nt
	v_lshl_add_u64 v[20:21], v[148:149], 1, v[154:155]
	v_pk_mul_f32 v[160:161], v[16:17], v[164:165] op_sel_hi:[1,0]
	v_pk_mul_f32 v[162:163], v[18:19], v[164:165] op_sel_hi:[1,0]
	v_exp_f32_e32 v160, v160
	v_exp_f32_e32 v161, v161
	v_exp_f32_e32 v162, v162
	v_exp_f32_e32 v163, v163
	v_pk_add_f32 v[160:161], v[160:161], 1.0 op_sel_hi:[1,0]
	v_pk_add_f32 v[162:163], v[162:163], 1.0 op_sel_hi:[1,0]
	v_rcp_f32_e32 v160, v160
	v_rcp_f32_e32 v161, v161
	v_rcp_f32_e32 v162, v162
	v_rcp_f32_e32 v163, v163
	v_pk_mul_f32 v[160:161], v[16:17], v[160:161]
	v_pk_mul_f32 v[162:163], v[18:19], v[162:163]
	v_pk_mul_f32 v[160:161], v[160:161], v[12:13]
	v_pk_mul_f32 v[162:163], v[162:163], v[14:15]
	v_cvt_pk_bf16_f32 v12, v160, v161
	v_cvt_pk_bf16_f32 v13, v162, v163
	v_pk_mul_f32 v[160:161], v[8:9], v[164:165] op_sel_hi:[1,0]
	v_pk_mul_f32 v[162:163], v[10:11], v[164:165] op_sel_hi:[1,0]
	v_exp_f32_e32 v160, v160
	v_exp_f32_e32 v161, v161
	v_exp_f32_e32 v162, v162
	v_exp_f32_e32 v163, v163
	v_pk_add_f32 v[160:161], v[160:161], 1.0 op_sel_hi:[1,0]
	v_pk_add_f32 v[162:163], v[162:163], 1.0 op_sel_hi:[1,0]
	v_rcp_f32_e32 v160, v160
	v_rcp_f32_e32 v161, v161
	v_rcp_f32_e32 v162, v162
	v_rcp_f32_e32 v163, v163
	v_pk_mul_f32 v[160:161], v[8:9], v[160:161]
	v_pk_mul_f32 v[162:163], v[10:11], v[162:163]
	v_pk_mul_f32 v[160:161], v[160:161], v[4:5]
	v_pk_mul_f32 v[162:163], v[162:163], v[6:7]
	v_cvt_pk_bf16_f32 v14, v160, v161
	v_cvt_pk_bf16_f32 v15, v162, v163
	global_store_dwordx4 v[20:21], v[12:15], off sc0 sc1 nt
	s_cbranch_vccnz .LBB0_740
	s_andn2_b64 vcc, exec, s[0:1]
	s_cbranch_vccnz .LBB0_739
	s_barrier
	s_branch .LBB0_739
